# EpiResid: group-3/4 t and stats loads hoisted one group early into spare VGPRs
# baseline (speedup 1.0000x reference)
;     __device__ __forceinline__ void operator()(const f32x4 (&acc)[2][2][4][2], const pg8::Unit& u, int wr, int wc, int, int) const { const int ln_ = lane_now(); const int fr = ln_ & 15, fq = ln_ >> 4;
;     ...
; #pragma unroll
;         for (int bj = 0; bj < 2; ++bj) { const int c = col0 + bj * 128;
;             const f32x4 gv0 = *(const f32x4*)(gate + (size_t)mi * NMOD + c), gv1 = *(const f32x4*)(gate + (size_t)mi * NMOD + c + 4);
;             const f32x4 g0 = *(const f32x4*)(lng + c) * DN_ALPHA, g1 = *(const f32x4*)(lng + c + 4) * DN_ALPHA, b0 = *(const f32x4*)(lnb + c) * DN_ALPHA, b1 = *(const f32x4*)(lnb + c + 4) * DN_ALPHA;
; #pragma unroll
;             for (int ai = 0; ai < 2; ++ai) {
;                 u32x4 tv[4]; f32x2 st[4];
; #pragma unroll
;                 for (int m = 0; m < 4; ++m) { const size_t row = (size_t)(upm * 256 + rl0 + ai * 128 + m * 16); tv[m] = *(const u32x4*)(H + row * D + c); st[m] = *(const f32x2*)(stats + row * 2); }
;                 asm volatile("s_waitcnt vmcnt(0)" ::: "memory");
; #pragma unroll
;                 for (int m = 0; m < 4; ++m) { const h16x4 ha = __builtin_bit_cast(h16x4, (u32x2){tv[m].x, tv[m].y}), hb = __builtin_bit_cast(h16x4, (u32x2){tv[m].z, tv[m].w});
;                     const f32x4 t0 = (f32x4){(float)ha[0], (float)ha[1], (float)ha[2], (float)ha[3]}, t1 = (f32x4){(float)hb[0], (float)hb[1], (float)hb[2], (float)hb[3]};
;                     const f32x4 o0 = (t0 - st[m].x) * st[m].y * g0 + b0 + gv0 * acc[ai][bj][m][0], o1 = (t1 - st[m].x) * st[m].y * g1 + b1 + gv1 * acc[ai][bj][m][1];
;                     h16x4 qa, qb; qa[0] = (_Float16)o0[0]; qa[1] = (_Float16)o0[1]; qa[2] = (_Float16)o0[2]; qa[3] = (_Float16)o0[3]; qb[0] = (_Float16)o1[0]; qb[1] = (_Float16)o1[1]; qb[2] = (_Float16)o1[2]; qb[3] = (_Float16)o1[3];
;                     const u32x2 pa = __builtin_bit_cast(u32x2, qa), pb = __builtin_bit_cast(u32x2, qb);
;                     *(u32x4*)(H + (size_t)(upm * 256 + rl0 + ai * 128 + m * 16) * D + c) = (u32x4){pa.x, pa.y, pb.x, pb.y}; } } }
.LBB0_1499:
	s_lshl_b64 s[2:3], s[2:3], 2
	s_add_u32 s2, s50, s2
	s_addc_u32 s3, s51, s3
	v_lshlrev_b64 v[148:149], 2, v[138:139]
	v_lshl_add_u64 v[152:153], s[2:3], 0, v[148:149]
	v_lshl_add_u64 v[156:157], s[4:5], 0, v[148:149]
	v_lshl_add_u32 v182, s70, 8, v140
	global_load_dwordx4 v[130:133], v[152:153], off offset:16
	global_load_dwordx4 v[134:137], v[152:153], off
	global_load_dwordx4 v[140:143], v[156:157], off offset:16
	global_load_dwordx4 v[144:147], v[156:157], off
	s_mov_b32 s2, 0x3fb504f3
	v_lshl_add_u64 v[150:151], s[6:7], 0, v[148:149]
	v_lshlrev_b64 v[176:177], 1, v[138:139]
	v_ashrrev_i32_e32 v183, 31, v182
	v_lshl_add_u64 v[184:185], s[10:11], 0, v[176:177]
	v_lshlrev_b64 v[208:209], 12, v[182:183]
	v_lshl_add_u64 v[138:139], v[184:185], 0, v[208:209]
	v_lshl_add_u64 v[154:155], v[182:183], 3, s[12:13]
	v_or_b32_e32 v170, 48, v182
	v_ashrrev_i32_e32 v171, 31, v170
	v_lshlrev_b64 v[188:189], 12, v[170:171]
	v_lshl_add_u64 v[170:171], v[170:171], 3, s[12:13]
	s_waitcnt vmcnt(1)
	v_pk_mul_f32 v[160:161], v[142:143], s[2:3] op_sel_hi:[1,0]
	s_waitcnt vmcnt(0)
	v_pk_mul_f32 v[166:167], v[146:147], s[2:3] op_sel_hi:[1,0]
	v_pk_mul_f32 v[168:169], v[144:145], s[2:3] op_sel_hi:[1,0]
	v_pk_mul_f32 v[164:165], v[140:141], s[2:3] op_sel_hi:[1,0]
	global_load_dwordx4 v[140:143], v[150:151], off offset:16
	global_load_dwordx4 v[144:147], v[150:151], off
	global_load_dwordx4 v[192:195], v[138:139], off
	global_load_dwordx2 v[196:197], v[154:155], off
	v_or_b32_e32 v138, 16, v182
	v_ashrrev_i32_e32 v139, 31, v138
	v_lshlrev_b64 v[190:191], 12, v[138:139]
	v_lshl_add_u64 v[162:163], v[138:139], 3, s[12:13]
	v_or_b32_e32 v138, 32, v182
	v_ashrrev_i32_e32 v139, 31, v138
	v_lshlrev_b64 v[186:187], 12, v[138:139]
	v_lshl_add_u64 v[158:159], v[138:139], 3, s[12:13]
	global_load_dwordx2 v[202:203], v[158:159], off
	v_lshl_add_u64 v[138:139], v[184:185], 0, v[188:189]
	global_load_dwordx2 v[206:207], v[162:163], off
	global_load_dwordx2 v[204:205], v[170:171], off
	s_waitcnt vmcnt(6)
	v_pk_mul_f32 v[174:175], v[140:141], s[2:3] op_sel_hi:[1,0]
	v_lshl_add_u64 v[140:141], v[184:185], 0, v[190:191]
	s_waitcnt vmcnt(5)
	v_pk_mul_f32 v[178:179], v[146:147], s[2:3] op_sel_hi:[1,0]
	global_load_dwordx4 v[146:149], v[140:141], off
	v_lshl_add_u64 v[140:141], v[184:185], 0, v[186:187]
	v_pk_mul_f32 v[180:181], v[144:145], s[2:3] op_sel_hi:[1,0]
	v_pk_mul_f32 v[172:173], v[142:143], s[2:3] op_sel_hi:[1,0]
	global_load_dwordx4 v[142:145], v[140:141], off
	s_waitcnt vmcnt(6)
	v_cvt_f32_f16_sdwa v183, v192 dst_sel:DWORD dst_unused:UNUSED_PAD src0_sel:WORD_1
	global_load_dwordx4 v[138:141], v[138:139], off
	v_cvt_f32_f16_e32 v192, v192
	v_cvt_f32_f16_sdwa v198, v193 dst_sel:DWORD dst_unused:UNUSED_PAD src0_sel:WORD_1
	v_cvt_f32_f16_e32 v199, v193
	v_cvt_f32_f16_sdwa v201, v194 dst_sel:DWORD dst_unused:UNUSED_PAD src0_sel:WORD_1
	v_cvt_f32_f16_e32 v214, v194
	v_cvt_f32_f16_sdwa v215, v195 dst_sel:DWORD dst_unused:UNUSED_PAD src0_sel:WORD_1
	v_cvt_f32_f16_e32 v216, v195
	s_waitcnt vmcnt(6)
	v_sub_f32_e32 v192, v192, v196
	v_sub_f32_e32 v193, v183, v196
	v_sub_f32_e32 v194, v199, v196
	v_sub_f32_e32 v195, v198, v196
	v_pk_mul_f32 v[192:193], v[196:197], v[192:193] op_sel:[1,0]
	v_pk_mul_f32 v[194:195], v[196:197], v[194:195] op_sel:[1,0]
	v_pk_fma_f32 v[192:193], v[168:169], v[192:193], v[180:181]
	v_pk_fma_f32 v[194:195], v[166:167], v[194:195], v[178:179]
	v_pk_fma_f32 v[126:127], v[126:127], v[134:135], v[192:193]
	v_sub_f32_e32 v192, v214, v196
	v_sub_f32_e32 v193, v201, v196
	v_pk_fma_f32 v[128:129], v[128:129], v[136:137], v[194:195]
	v_sub_f32_e32 v194, v216, v196
	v_sub_f32_e32 v195, v215, v196
	v_pk_mul_f32 v[192:193], v[196:197], v[192:193] op_sel:[1,0]
	v_pk_mul_f32 v[194:195], v[196:197], v[194:195] op_sel:[1,0]
	v_pk_fma_f32 v[192:193], v[164:165], v[192:193], v[174:175]
	v_pk_fma_f32 v[194:195], v[160:161], v[194:195], v[172:173]
	v_pk_fma_f32 v[122:123], v[122:123], v[130:131], v[192:193]
	v_pk_fma_f32 v[194:195], v[124:125], v[132:133], v[194:195]
	v_cvt_pk_f16_f32 v124, v126, v127
	v_cvt_pk_f16_f32 v126, v122, v123
	v_lshl_add_u64 v[122:123], s[10:11], 0, v[208:209]
	v_cvt_pk_f16_f32 v125, v128, v129
	v_cvt_pk_f16_f32 v127, v194, v195
	v_lshl_add_u64 v[122:123], v[122:123], 0, v[176:177]
	s_waitcnt vmcnt(0)
	global_store_dwordx4 v[122:123], v[124:127], off
	s_waitcnt vmcnt(3)
	v_cvt_f32_f16_sdwa v128, v148 dst_sel:DWORD dst_unused:UNUSED_PAD src0_sel:WORD_1
	v_cvt_f32_f16_sdwa v125, v146 dst_sel:DWORD dst_unused:UNUSED_PAD src0_sel:WORD_1
	v_cvt_f32_f16_e32 v124, v146
	v_cvt_f32_f16_sdwa v127, v147 dst_sel:DWORD dst_unused:UNUSED_PAD src0_sel:WORD_1
	v_cvt_f32_f16_e32 v126, v147
	v_cvt_f32_f16_e32 v129, v148
	v_cvt_f32_f16_sdwa v146, v149 dst_sel:DWORD dst_unused:UNUSED_PAD src0_sel:WORD_1
	v_cvt_f32_f16_e32 v147, v149
	v_sub_f32_e32 v124, v124, v206
	v_sub_f32_e32 v125, v125, v206
	v_sub_f32_e32 v126, v126, v206
	v_sub_f32_e32 v127, v127, v206
	v_pk_mul_f32 v[124:125], v[206:207], v[124:125] op_sel:[1,0]
	v_pk_mul_f32 v[126:127], v[206:207], v[126:127] op_sel:[1,0]
	v_pk_fma_f32 v[124:125], v[168:169], v[124:125], v[180:181]
	v_pk_fma_f32 v[126:127], v[166:167], v[126:127], v[178:179]
	v_pk_fma_f32 v[118:119], v[118:119], v[134:135], v[124:125]
	v_sub_f32_e32 v124, v129, v206
	v_sub_f32_e32 v125, v128, v206
	v_pk_fma_f32 v[120:121], v[120:121], v[136:137], v[126:127]
	v_sub_f32_e32 v126, v147, v206
	v_sub_f32_e32 v127, v146, v206
	v_pk_mul_f32 v[124:125], v[206:207], v[124:125] op_sel:[1,0]
	v_pk_mul_f32 v[126:127], v[206:207], v[126:127] op_sel:[1,0]
	v_pk_fma_f32 v[124:125], v[164:165], v[124:125], v[174:175]
	v_pk_fma_f32 v[126:127], v[160:161], v[126:127], v[172:173]
	v_pk_fma_f32 v[114:115], v[114:115], v[130:131], v[124:125]
	v_pk_fma_f32 v[126:127], v[116:117], v[132:133], v[126:127]
	v_cvt_pk_f16_f32 v116, v118, v119
	v_cvt_pk_f16_f32 v118, v114, v115
	v_lshl_add_u64 v[114:115], s[10:11], 0, v[190:191]
	v_cvt_pk_f16_f32 v117, v120, v121
	v_cvt_pk_f16_f32 v119, v126, v127
	v_lshl_add_u64 v[114:115], v[114:115], 0, v[176:177]
	global_store_dwordx4 v[114:115], v[116:119], off
	s_waitcnt vmcnt(3)
;     __device__ __forceinline__ void operator()(const f32x4 (&acc)[2][2][4][2], const pg8::Unit& u, int wr, int wc, int, int) const { const int ln_ = lane_now(); const int fr = ln_ & 15, fq = ln_ >> 4;
;     ...
;                 for (int m = 0; m < 4; ++m) { const size_t row = (size_t)(upm * 256 + rl0 + ai * 128 + m * 16); tv[m] = *(const u32x4*)(H + row * D + c); st[m] = *(const f32x2*)(stats + row * 2); }
;                 asm volatile("s_waitcnt vmcnt(0)" ::: "memory");
; #pragma unroll
;                 for (int m = 0; m < 4; ++m) { const h16x4 ha = __builtin_bit_cast(h16x4, (u32x2){tv[m].x, tv[m].y}), hb = __builtin_bit_cast(h16x4, (u32x2){tv[m].z, tv[m].w});
;                     const f32x4 t0 = (f32x4){(float)ha[0], (float)ha[1], (float)ha[2], (float)ha[3]}, t1 = (f32x4){(float)hb[0], (float)hb[1], (float)hb[2], (float)hb[3]};
;                     const f32x4 o0 = (t0 - st[m].x) * st[m].y * g0 + b0 + gv0 * acc[ai][bj][m][0], o1 = (t1 - st[m].x) * st[m].y * g1 + b1 + gv1 * acc[ai][bj][m][1];
;                     h16x4 qa, qb; qa[0] = (_Float16)o0[0]; qa[1] = (_Float16)o0[1]; qa[2] = (_Float16)o0[2]; qa[3] = (_Float16)o0[3]; qb[0] = (_Float16)o1[0]; qb[1] = (_Float16)o1[1]; qb[2] = (_Float16)o1[2]; qb[3] = (_Float16)o1[3];
;                     const u32x2 pa = __builtin_bit_cast(u32x2, qa), pb = __builtin_bit_cast(u32x2, qb);
;                     *(u32x4*)(H + (size_t)(upm * 256 + rl0 + ai * 128 + m * 16) * D + c) = (u32x4){pa.x, pa.y, pb.x, pb.y}; } } }
	v_cvt_f32_f16_sdwa v120, v144 dst_sel:DWORD dst_unused:UNUSED_PAD src0_sel:WORD_1
	v_cvt_f32_f16_e32 v121, v144
	v_cvt_f32_f16_sdwa v117, v142 dst_sel:DWORD dst_unused:UNUSED_PAD src0_sel:WORD_1
	v_cvt_f32_f16_e32 v116, v142
	v_cvt_f32_f16_sdwa v119, v143 dst_sel:DWORD dst_unused:UNUSED_PAD src0_sel:WORD_1
	v_cvt_f32_f16_e32 v118, v143
	v_cvt_f32_f16_sdwa v124, v145 dst_sel:DWORD dst_unused:UNUSED_PAD src0_sel:WORD_1
	v_cvt_f32_f16_e32 v125, v145
	v_sub_f32_e32 v116, v116, v202
	v_sub_f32_e32 v117, v117, v202
	v_sub_f32_e32 v118, v118, v202
	v_sub_f32_e32 v119, v119, v202
	v_pk_mul_f32 v[116:117], v[202:203], v[116:117] op_sel:[1,0]
	v_pk_mul_f32 v[118:119], v[202:203], v[118:119] op_sel:[1,0]
	v_pk_fma_f32 v[116:117], v[168:169], v[116:117], v[180:181]
	v_pk_fma_f32 v[118:119], v[166:167], v[118:119], v[178:179]
	v_pk_fma_f32 v[110:111], v[110:111], v[134:135], v[116:117]
	v_sub_f32_e32 v116, v121, v202
	v_sub_f32_e32 v117, v120, v202
	v_pk_fma_f32 v[112:113], v[112:113], v[136:137], v[118:119]
	v_sub_f32_e32 v118, v125, v202
	v_sub_f32_e32 v119, v124, v202
	v_pk_mul_f32 v[116:117], v[202:203], v[116:117] op_sel:[1,0]
	v_pk_mul_f32 v[118:119], v[202:203], v[118:119] op_sel:[1,0]
	v_pk_fma_f32 v[116:117], v[164:165], v[116:117], v[174:175]
	v_pk_fma_f32 v[118:119], v[160:161], v[118:119], v[172:173]
	v_pk_fma_f32 v[106:107], v[106:107], v[130:131], v[116:117]
	v_pk_fma_f32 v[118:119], v[108:109], v[132:133], v[118:119]
	v_cvt_pk_f16_f32 v108, v110, v111
	v_cvt_pk_f16_f32 v110, v106, v107
	v_lshl_add_u64 v[106:107], s[10:11], 0, v[186:187]
	v_cvt_pk_f16_f32 v109, v112, v113
	v_cvt_pk_f16_f32 v111, v118, v119
	v_lshl_add_u64 v[106:107], v[106:107], 0, v[176:177]
	global_store_dwordx4 v[106:107], v[108:111], off
	s_waitcnt vmcnt(3)
	v_cvt_f32_f16_sdwa v112, v140 dst_sel:DWORD dst_unused:UNUSED_PAD src0_sel:WORD_1
	v_cvt_f32_f16_e32 v113, v140
	v_cvt_f32_f16_sdwa v109, v138 dst_sel:DWORD dst_unused:UNUSED_PAD src0_sel:WORD_1
	v_cvt_f32_f16_e32 v108, v138
	v_cvt_f32_f16_sdwa v111, v139 dst_sel:DWORD dst_unused:UNUSED_PAD src0_sel:WORD_1
	v_cvt_f32_f16_e32 v110, v139
	v_cvt_f32_f16_sdwa v116, v141 dst_sel:DWORD dst_unused:UNUSED_PAD src0_sel:WORD_1
	v_cvt_f32_f16_e32 v117, v141
	v_sub_f32_e32 v108, v108, v204
	v_sub_f32_e32 v109, v109, v204
	v_sub_f32_e32 v110, v110, v204
	v_sub_f32_e32 v111, v111, v204
	v_pk_mul_f32 v[108:109], v[204:205], v[108:109] op_sel:[1,0]
	v_pk_mul_f32 v[110:111], v[204:205], v[110:111] op_sel:[1,0]
	v_pk_fma_f32 v[108:109], v[168:169], v[108:109], v[180:181]
	v_pk_fma_f32 v[110:111], v[166:167], v[110:111], v[178:179]
	v_pk_fma_f32 v[108:109], v[102:103], v[134:135], v[108:109]
	v_sub_f32_e32 v102, v113, v204
	v_sub_f32_e32 v103, v112, v204
	v_pk_fma_f32 v[104:105], v[104:105], v[136:137], v[110:111]
	v_sub_f32_e32 v110, v117, v204
	v_sub_f32_e32 v111, v116, v204
	v_pk_mul_f32 v[102:103], v[204:205], v[102:103] op_sel:[1,0]
	v_pk_mul_f32 v[110:111], v[204:205], v[110:111] op_sel:[1,0]
	v_pk_fma_f32 v[102:103], v[164:165], v[102:103], v[174:175]
	v_pk_fma_f32 v[110:111], v[160:161], v[110:111], v[172:173]
	v_pk_fma_f32 v[98:99], v[98:99], v[130:131], v[102:103]
	v_pk_fma_f32 v[100:101], v[100:101], v[132:133], v[110:111]
	v_cvt_pk_f16_f32 v103, v104, v105
	v_cvt_pk_f16_f32 v104, v98, v99
	v_lshl_add_u64 v[98:99], s[10:11], 0, v[188:189]
	v_cvt_pk_f16_f32 v105, v100, v101
	v_lshl_add_u64 v[100:101], v[98:99], 0, v[176:177]
	v_add_u32_e32 v98, 0x80, v182
	v_ashrrev_i32_e32 v99, 31, v98
	v_cvt_pk_f16_f32 v102, v108, v109
	v_lshlrev_b64 v[120:121], 12, v[98:99]
	global_store_dwordx4 v[100:101], v[102:105], off
	v_lshl_add_u64 v[98:99], v[98:99], 3, s[12:13]
	global_load_dwordx2 v[128:129], v[98:99], off
	v_lshl_add_u64 v[102:103], v[184:185], 0, v[120:121]
	global_load_dwordx4 v[110:113], v[102:103], off
	v_add_u32_e32 v102, 0x90, v182
	v_ashrrev_i32_e32 v103, 31, v102
	v_lshlrev_b64 v[142:143], 12, v[102:103]
	v_lshl_add_u64 v[104:105], v[184:185], 0, v[142:143]
	global_load_dwordx4 v[116:119], v[104:105], off
	v_lshl_add_u64 v[102:103], v[102:103], 3, s[12:13]
	global_load_dwordx2 v[144:145], v[102:103], off
	v_add_u32_e32 v104, 0xa0, v182
	v_ashrrev_i32_e32 v105, 31, v104
	v_lshlrev_b64 v[146:147], 12, v[104:105]
	v_lshl_add_u64 v[108:109], v[184:185], 0, v[146:147]
	global_load_dwordx4 v[124:127], v[108:109], off
	v_lshl_add_u64 v[104:105], v[104:105], 3, s[12:13]
	global_load_dwordx2 v[148:149], v[104:105], off
	v_add_u32_e32 v108, 0xb0, v182
	v_ashrrev_i32_e32 v109, 31, v108
	v_lshlrev_b64 v[182:183], 12, v[108:109]
	v_lshl_add_u64 v[138:139], v[184:185], 0, v[182:183]
	global_load_dwordx4 v[138:141], v[138:139], off
	v_lshl_add_u64 v[108:109], v[108:109], 3, s[12:13]
	global_load_dwordx2 v[184:185], v[108:109], off
	global_load_dwordx4 v[240:243], v[122:123], off offset:256
	global_load_dwordx2 v[226:227], v[154:155], off
	global_load_dwordx4 v[244:247], v[114:115], off offset:256
	global_load_dwordx2 v[228:229], v[162:163], off
	global_load_dwordx4 v[248:251], v[106:107], off offset:256
	global_load_dwordx2 v[236:237], v[158:159], off
	global_load_dwordx4 v[232:235], v[100:101], off offset:256
	global_load_dword v238, v[170:171], off
	global_load_dword v217, v[170:171], off offset:4
	s_waitcnt vmcnt(0)
	s_waitcnt vmcnt(6)
;     __device__ __forceinline__ void operator()(const f32x4 (&acc)[2][2][4][2], const pg8::Unit& u, int wr, int wc, int, int) const { const int ln_ = lane_now(); const int fr = ln_ & 15, fq = ln_ >> 4;
;     ...
; #pragma unroll
;                 for (int m = 0; m < 4; ++m) { const h16x4 ha = __builtin_bit_cast(h16x4, (u32x2){tv[m].x, tv[m].y}), hb = __builtin_bit_cast(h16x4, (u32x2){tv[m].z, tv[m].w});
;                     const f32x4 t0 = (f32x4){(float)ha[0], (float)ha[1], (float)ha[2], (float)ha[3]}, t1 = (f32x4){(float)hb[0], (float)hb[1], (float)hb[2], (float)hb[3]};
;                     const f32x4 o0 = (t0 - st[m].x) * st[m].y * g0 + b0 + gv0 * acc[ai][bj][m][0], o1 = (t1 - st[m].x) * st[m].y * g1 + b1 + gv1 * acc[ai][bj][m][1];
;                     h16x4 qa, qb; qa[0] = (_Float16)o0[0]; qa[1] = (_Float16)o0[1]; qa[2] = (_Float16)o0[2]; qa[3] = (_Float16)o0[3]; qb[0] = (_Float16)o1[0]; qb[1] = (_Float16)o1[1]; qb[2] = (_Float16)o1[2]; qb[3] = (_Float16)o1[3];
;                     const u32x2 pa = __builtin_bit_cast(u32x2, qa), pb = __builtin_bit_cast(u32x2, qb);
;                     *(u32x4*)(H + (size_t)(upm * 256 + rl0 + ai * 128 + m * 16) * D + c) = (u32x4){pa.x, pa.y, pb.x, pb.y}; } } }
	v_cvt_f32_f16_e32 v186, v110
	v_cvt_f32_f16_sdwa v110, v110 dst_sel:DWORD dst_unused:UNUSED_PAD src0_sel:WORD_1
	v_cvt_f32_f16_e32 v187, v111
	v_cvt_f32_f16_sdwa v188, v111 dst_sel:DWORD dst_unused:UNUSED_PAD src0_sel:WORD_1
	v_cvt_f32_f16_e32 v189, v112
	v_cvt_f32_f16_sdwa v190, v112 dst_sel:DWORD dst_unused:UNUSED_PAD src0_sel:WORD_1
	v_cvt_f32_f16_e32 v191, v113
	v_cvt_f32_f16_sdwa v192, v113 dst_sel:DWORD dst_unused:UNUSED_PAD src0_sel:WORD_1
	v_sub_f32_e32 v111, v110, v128
	v_sub_f32_e32 v110, v186, v128
	v_sub_f32_e32 v113, v188, v128
	v_sub_f32_e32 v112, v187, v128
	v_pk_mul_f32 v[110:111], v[128:129], v[110:111] op_sel:[1,0]
	v_pk_mul_f32 v[112:113], v[128:129], v[112:113] op_sel:[1,0]
	v_pk_fma_f32 v[110:111], v[168:169], v[110:111], v[180:181]
	v_pk_fma_f32 v[112:113], v[166:167], v[112:113], v[178:179]
	v_pk_fma_f32 v[94:95], v[94:95], v[134:135], v[110:111]
	v_sub_f32_e32 v111, v190, v128
	v_sub_f32_e32 v110, v189, v128
	v_pk_fma_f32 v[96:97], v[96:97], v[136:137], v[112:113]
	v_sub_f32_e32 v113, v192, v128
	v_sub_f32_e32 v112, v191, v128
	v_pk_mul_f32 v[110:111], v[128:129], v[110:111] op_sel:[1,0]
	v_pk_mul_f32 v[112:113], v[128:129], v[112:113] op_sel:[1,0]
	v_pk_fma_f32 v[110:111], v[164:165], v[110:111], v[174:175]
	v_pk_fma_f32 v[112:113], v[160:161], v[112:113], v[172:173]
	v_pk_fma_f32 v[90:91], v[90:91], v[130:131], v[110:111]
	v_pk_fma_f32 v[112:113], v[92:93], v[132:133], v[112:113]
	v_cvt_pk_f16_f32 v92, v94, v95
	v_cvt_pk_f16_f32 v94, v90, v91
	v_lshl_add_u64 v[90:91], s[10:11], 0, v[120:121]
	v_cvt_pk_f16_f32 v93, v96, v97
	v_cvt_pk_f16_f32 v95, v112, v113
	v_lshl_add_u64 v[90:91], v[90:91], 0, v[176:177]
	global_store_dwordx4 v[90:91], v[92:95], off
	s_waitcnt vmcnt(6)
	v_cvt_f32_f16_e32 v96, v118
	v_cvt_f32_f16_sdwa v97, v118 dst_sel:DWORD dst_unused:UNUSED_PAD src0_sel:WORD_1
	v_cvt_f32_f16_e32 v92, v116
	v_cvt_f32_f16_sdwa v93, v116 dst_sel:DWORD dst_unused:UNUSED_PAD src0_sel:WORD_1
	v_cvt_f32_f16_e32 v94, v117
	v_cvt_f32_f16_sdwa v95, v117 dst_sel:DWORD dst_unused:UNUSED_PAD src0_sel:WORD_1
	v_cvt_f32_f16_e32 v110, v119
	v_cvt_f32_f16_sdwa v111, v119 dst_sel:DWORD dst_unused:UNUSED_PAD src0_sel:WORD_1
	s_waitcnt vmcnt(5)
	v_sub_f32_e32 v93, v93, v144
	v_sub_f32_e32 v92, v92, v144
	v_sub_f32_e32 v95, v95, v144
	v_sub_f32_e32 v94, v94, v144
	v_pk_mul_f32 v[92:93], v[144:145], v[92:93] op_sel:[1,0]
	v_pk_mul_f32 v[94:95], v[144:145], v[94:95] op_sel:[1,0]
	v_pk_fma_f32 v[92:93], v[168:169], v[92:93], v[180:181]
	v_pk_fma_f32 v[94:95], v[166:167], v[94:95], v[178:179]
	v_pk_fma_f32 v[86:87], v[86:87], v[134:135], v[92:93]
	v_sub_f32_e32 v93, v97, v144
	v_sub_f32_e32 v92, v96, v144
	v_pk_fma_f32 v[88:89], v[88:89], v[136:137], v[94:95]
	v_sub_f32_e32 v95, v111, v144
	v_sub_f32_e32 v94, v110, v144
	v_pk_mul_f32 v[92:93], v[144:145], v[92:93] op_sel:[1,0]
	v_pk_mul_f32 v[94:95], v[144:145], v[94:95] op_sel:[1,0]
	v_pk_fma_f32 v[92:93], v[164:165], v[92:93], v[174:175]
	v_pk_fma_f32 v[94:95], v[160:161], v[94:95], v[172:173]
	v_pk_fma_f32 v[82:83], v[82:83], v[130:131], v[92:93]
	v_pk_fma_f32 v[94:95], v[84:85], v[132:133], v[94:95]
	v_cvt_pk_f16_f32 v84, v86, v87
	v_cvt_pk_f16_f32 v86, v82, v83
	v_lshl_add_u64 v[82:83], s[10:11], 0, v[142:143]
	v_cvt_pk_f16_f32 v85, v88, v89
	v_cvt_pk_f16_f32 v87, v94, v95
	v_lshl_add_u64 v[82:83], v[82:83], 0, v[176:177]
	global_store_dwordx4 v[82:83], v[84:87], off
	s_waitcnt vmcnt(5)
	v_cvt_f32_f16_e32 v88, v126
	v_cvt_f32_f16_sdwa v89, v126 dst_sel:DWORD dst_unused:UNUSED_PAD src0_sel:WORD_1
	v_cvt_f32_f16_e32 v84, v124
	v_cvt_f32_f16_sdwa v85, v124 dst_sel:DWORD dst_unused:UNUSED_PAD src0_sel:WORD_1
	v_cvt_f32_f16_e32 v86, v125
	v_cvt_f32_f16_sdwa v87, v125 dst_sel:DWORD dst_unused:UNUSED_PAD src0_sel:WORD_1
	v_cvt_f32_f16_e32 v92, v127
	v_cvt_f32_f16_sdwa v93, v127 dst_sel:DWORD dst_unused:UNUSED_PAD src0_sel:WORD_1
	s_waitcnt vmcnt(4)
	v_sub_f32_e32 v85, v85, v148
	v_sub_f32_e32 v84, v84, v148
	v_sub_f32_e32 v87, v87, v148
	v_sub_f32_e32 v86, v86, v148
	v_pk_mul_f32 v[84:85], v[148:149], v[84:85] op_sel:[1,0]
	v_pk_mul_f32 v[86:87], v[148:149], v[86:87] op_sel:[1,0]
	v_pk_fma_f32 v[84:85], v[168:169], v[84:85], v[180:181]
	v_pk_fma_f32 v[86:87], v[166:167], v[86:87], v[178:179]
	v_pk_fma_f32 v[78:79], v[78:79], v[134:135], v[84:85]
	v_sub_f32_e32 v85, v89, v148
	v_sub_f32_e32 v84, v88, v148
	v_pk_fma_f32 v[80:81], v[80:81], v[136:137], v[86:87]
	v_sub_f32_e32 v87, v93, v148
	v_sub_f32_e32 v86, v92, v148
	v_pk_mul_f32 v[84:85], v[148:149], v[84:85] op_sel:[1,0]
	v_pk_mul_f32 v[86:87], v[148:149], v[86:87] op_sel:[1,0]
	v_pk_fma_f32 v[84:85], v[164:165], v[84:85], v[174:175]
	v_pk_fma_f32 v[86:87], v[160:161], v[86:87], v[172:173]
	v_pk_fma_f32 v[74:75], v[74:75], v[130:131], v[84:85]
	v_pk_fma_f32 v[86:87], v[76:77], v[132:133], v[86:87]
	v_cvt_pk_f16_f32 v76, v78, v79
	v_cvt_pk_f16_f32 v78, v74, v75
	v_lshl_add_u64 v[74:75], s[10:11], 0, v[146:147]
	v_cvt_pk_f16_f32 v77, v80, v81
	v_cvt_pk_f16_f32 v79, v86, v87
	v_lshl_add_u64 v[74:75], v[74:75], 0, v[176:177]
	global_store_dwordx4 v[74:75], v[76:79], off
	s_waitcnt vmcnt(4)
	v_cvt_f32_f16_e32 v80, v140
	v_cvt_f32_f16_sdwa v81, v140 dst_sel:DWORD dst_unused:UNUSED_PAD src0_sel:WORD_1
	v_cvt_f32_f16_e32 v76, v138
	v_cvt_f32_f16_sdwa v77, v138 dst_sel:DWORD dst_unused:UNUSED_PAD src0_sel:WORD_1
	v_cvt_f32_f16_e32 v78, v139
	v_cvt_f32_f16_sdwa v79, v139 dst_sel:DWORD dst_unused:UNUSED_PAD src0_sel:WORD_1
	v_cvt_f32_f16_e32 v84, v141
	v_cvt_f32_f16_sdwa v85, v141 dst_sel:DWORD dst_unused:UNUSED_PAD src0_sel:WORD_1
	s_waitcnt vmcnt(3)
;     __device__ __forceinline__ void operator()(const f32x4 (&acc)[2][2][4][2], const pg8::Unit& u, int wr, int wc, int, int) const { const int ln_ = lane_now(); const int fr = ln_ & 15, fq = ln_ >> 4;
;     ...
;         for (int bj = 0; bj < 2; ++bj) { const int c = col0 + bj * 128;
;             const f32x4 gv0 = *(const f32x4*)(gate + (size_t)mi * NMOD + c), gv1 = *(const f32x4*)(gate + (size_t)mi * NMOD + c + 4);
;             const f32x4 g0 = *(const f32x4*)(lng + c) * DN_ALPHA, g1 = *(const f32x4*)(lng + c + 4) * DN_ALPHA, b0 = *(const f32x4*)(lnb + c) * DN_ALPHA, b1 = *(const f32x4*)(lnb + c + 4) * DN_ALPHA;
; #pragma unroll
;             for (int ai = 0; ai < 2; ++ai) {
;                 u32x4 tv[4]; f32x2 st[4];
; #pragma unroll
;                 for (int m = 0; m < 4; ++m) { const size_t row = (size_t)(upm * 256 + rl0 + ai * 128 + m * 16); tv[m] = *(const u32x4*)(H + row * D + c); st[m] = *(const f32x2*)(stats + row * 2); }
;                 asm volatile("s_waitcnt vmcnt(0)" ::: "memory");
; #pragma unroll
;                 for (int m = 0; m < 4; ++m) { const h16x4 ha = __builtin_bit_cast(h16x4, (u32x2){tv[m].x, tv[m].y}), hb = __builtin_bit_cast(h16x4, (u32x2){tv[m].z, tv[m].w});
;                     const f32x4 t0 = (f32x4){(float)ha[0], (float)ha[1], (float)ha[2], (float)ha[3]}, t1 = (f32x4){(float)hb[0], (float)hb[1], (float)hb[2], (float)hb[3]};
;                     const f32x4 o0 = (t0 - st[m].x) * st[m].y * g0 + b0 + gv0 * acc[ai][bj][m][0], o1 = (t1 - st[m].x) * st[m].y * g1 + b1 + gv1 * acc[ai][bj][m][1];
;                     h16x4 qa, qb; qa[0] = (_Float16)o0[0]; qa[1] = (_Float16)o0[1]; qa[2] = (_Float16)o0[2]; qa[3] = (_Float16)o0[3]; qb[0] = (_Float16)o1[0]; qb[1] = (_Float16)o1[1]; qb[2] = (_Float16)o1[2]; qb[3] = (_Float16)o1[3];
;                     const u32x2 pa = __builtin_bit_cast(u32x2, qa), pb = __builtin_bit_cast(u32x2, qb);
;                     *(u32x4*)(H + (size_t)(upm * 256 + rl0 + ai * 128 + m * 16) * D + c) = (u32x4){pa.x, pa.y, pb.x, pb.y}; } } }
	v_sub_f32_e32 v77, v77, v184
	v_sub_f32_e32 v76, v76, v184
	v_sub_f32_e32 v79, v79, v184
	v_sub_f32_e32 v78, v78, v184
	v_pk_mul_f32 v[78:79], v[184:185], v[78:79] op_sel:[1,0]
	v_pk_mul_f32 v[76:77], v[184:185], v[76:77] op_sel:[1,0]
	v_pk_fma_f32 v[78:79], v[166:167], v[78:79], v[178:179]
	v_pk_fma_f32 v[76:77], v[168:169], v[76:77], v[180:181]
	v_pk_fma_f32 v[72:73], v[72:73], v[136:137], v[78:79]
	v_pk_fma_f32 v[70:71], v[70:71], v[134:135], v[76:77]
	v_sub_f32_e32 v77, v81, v184
	v_sub_f32_e32 v76, v80, v184
	v_sub_f32_e32 v79, v85, v184
	v_sub_f32_e32 v78, v84, v184
	v_pk_mul_f32 v[78:79], v[184:185], v[78:79] op_sel:[1,0]
	v_pk_mul_f32 v[76:77], v[184:185], v[76:77] op_sel:[1,0]
	v_pk_fma_f32 v[78:79], v[160:161], v[78:79], v[172:173]
	v_pk_fma_f32 v[76:77], v[164:165], v[76:77], v[174:175]
	v_pk_fma_f32 v[68:69], v[68:69], v[132:133], v[78:79]
	v_pk_fma_f32 v[76:77], v[66:67], v[130:131], v[76:77]
	v_cvt_pk_f16_f32 v66, v70, v71
	v_lshl_add_u64 v[70:71], s[10:11], 0, v[182:183]
	v_cvt_pk_f16_f32 v67, v72, v73
	v_cvt_pk_f16_f32 v69, v68, v69
	v_cvt_pk_f16_f32 v68, v76, v77
	v_lshl_add_u64 v[76:77], v[70:71], 0, v[176:177]
	global_store_dwordx4 v[76:77], v[66:69], off
	global_load_dwordx4 v[66:69], v[152:153], off offset:528
	s_nop 0
	global_load_dwordx4 v[70:73], v[152:153], off offset:512
	global_load_dwordx4 v[92:95], v[156:157], off offset:528
	global_load_dwordx4 v[78:81], v[156:157], off offset:512
	s_waitcnt vmcnt(0)
	v_pk_mul_f32 v[84:85], v[80:81], s[2:3] op_sel_hi:[1,0]
	v_pk_mul_f32 v[86:87], v[78:79], s[2:3] op_sel_hi:[1,0]
	v_pk_mul_f32 v[78:79], v[94:95], s[2:3] op_sel_hi:[1,0]
	v_pk_mul_f32 v[80:81], v[92:93], s[2:3] op_sel_hi:[1,0]
	global_load_dwordx4 v[110:113], v[150:151], off offset:528
	global_load_dwordx4 v[92:95], v[150:151], off offset:512
	s_waitcnt vmcnt(1)
	v_pk_mul_f32 v[88:89], v[112:113], s[2:3] op_sel_hi:[1,0]
	s_waitcnt vmcnt(0)
	v_pk_mul_f32 v[96:97], v[92:93], s[2:3] op_sel_hi:[1,0]
	v_pk_mul_f32 v[92:93], v[110:111], s[2:3] op_sel_hi:[1,0]
	v_mov_b32_e32 v110, v240
	v_mov_b32_e32 v111, v241
	v_mov_b32_e32 v112, v242
	v_mov_b32_e32 v113, v243
	v_mov_b32_e32 v120, v226
	v_mov_b32_e32 v121, v227
	v_mov_b32_e32 v116, v244
	v_mov_b32_e32 v117, v245
	v_mov_b32_e32 v118, v246
	v_mov_b32_e32 v119, v247
	v_mov_b32_e32 v132, v228
	v_mov_b32_e32 v133, v229
	v_mov_b32_e32 v124, v248
	v_mov_b32_e32 v125, v249
	v_mov_b32_e32 v126, v250
	v_mov_b32_e32 v127, v251
	v_mov_b32_e32 v134, v236
	v_mov_b32_e32 v135, v237
	v_mov_b32_e32 v128, v232
	v_mov_b32_e32 v129, v233
	v_mov_b32_e32 v130, v234
	v_mov_b32_e32 v131, v235
	v_mov_b32_e32 v136, v238
	v_mov_b32_e32 v137, v217
	global_load_dwordx4 v[240:243], v[90:91], off offset:256
	global_load_dwordx2 v[226:227], v[98:99], off
	global_load_dwordx4 v[244:247], v[82:83], off offset:256
	global_load_dwordx2 v[228:229], v[102:103], off
	global_load_dwordx4 v[248:251], v[74:75], off offset:256
	global_load_dwordx2 v[236:237], v[104:105], off
	global_load_dwordx4 v[232:235], v[76:77], off offset:256
	global_load_dword v238, v[108:109], off
	global_load_dword v217, v[108:109], off offset:4
	v_pk_mul_f32 v[94:95], v[94:95], s[2:3] op_sel_hi:[1,0]
	v_cvt_f32_f16_e32 v138, v110
	v_cvt_f32_f16_sdwa v110, v110 dst_sel:DWORD dst_unused:UNUSED_PAD src0_sel:WORD_1
	v_cvt_f32_f16_e32 v139, v111
	v_cvt_f32_f16_sdwa v140, v111 dst_sel:DWORD dst_unused:UNUSED_PAD src0_sel:WORD_1
	v_cvt_f32_f16_e32 v141, v112
	v_cvt_f32_f16_sdwa v142, v112 dst_sel:DWORD dst_unused:UNUSED_PAD src0_sel:WORD_1
	v_cvt_f32_f16_e32 v143, v113
	v_cvt_f32_f16_sdwa v144, v113 dst_sel:DWORD dst_unused:UNUSED_PAD src0_sel:WORD_1
	v_sub_f32_e32 v111, v110, v120
	v_sub_f32_e32 v110, v138, v120
	v_sub_f32_e32 v113, v140, v120
	v_sub_f32_e32 v112, v139, v120
	v_pk_mul_f32 v[112:113], v[120:121], v[112:113] op_sel:[1,0]
	v_pk_mul_f32 v[110:111], v[120:121], v[110:111] op_sel:[1,0]
	v_pk_fma_f32 v[112:113], v[84:85], v[112:113], v[94:95]
	v_pk_fma_f32 v[110:111], v[86:87], v[110:111], v[96:97]
	v_pk_fma_f32 v[64:65], v[64:65], v[72:73], v[112:113]
	v_pk_fma_f32 v[62:63], v[62:63], v[70:71], v[110:111]
	v_sub_f32_e32 v111, v142, v120
	v_sub_f32_e32 v110, v141, v120
	v_sub_f32_e32 v113, v144, v120
	v_sub_f32_e32 v112, v143, v120
	v_pk_mul_f32 v[112:113], v[120:121], v[112:113] op_sel:[1,0]
	v_pk_mul_f32 v[110:111], v[120:121], v[110:111] op_sel:[1,0]
	v_pk_fma_f32 v[112:113], v[78:79], v[112:113], v[88:89]
	v_pk_fma_f32 v[110:111], v[80:81], v[110:111], v[92:93]
	v_pk_fma_f32 v[60:61], v[60:61], v[68:69], v[112:113]
	v_pk_fma_f32 v[110:111], v[58:59], v[66:67], v[110:111]
	v_cvt_pk_f16_f32 v59, v64, v65
	v_cvt_pk_f16_f32 v58, v62, v63
	v_cvt_pk_f16_f32 v61, v60, v61
	v_cvt_pk_f16_f32 v60, v110, v111
	global_store_dwordx4 v[122:123], v[58:61], off offset:256
	v_cvt_f32_f16_e32 v62, v118
	v_cvt_f32_f16_sdwa v63, v118 dst_sel:DWORD dst_unused:UNUSED_PAD src0_sel:WORD_1
	v_cvt_f32_f16_e32 v58, v116
	v_cvt_f32_f16_sdwa v59, v116 dst_sel:DWORD dst_unused:UNUSED_PAD src0_sel:WORD_1
	v_cvt_f32_f16_e32 v60, v117
	v_cvt_f32_f16_sdwa v61, v117 dst_sel:DWORD dst_unused:UNUSED_PAD src0_sel:WORD_1
	v_cvt_f32_f16_e32 v64, v119
	v_cvt_f32_f16_sdwa v65, v119 dst_sel:DWORD dst_unused:UNUSED_PAD src0_sel:WORD_1
	v_sub_f32_e32 v59, v59, v132
	v_sub_f32_e32 v58, v58, v132
	v_sub_f32_e32 v61, v61, v132
	v_sub_f32_e32 v60, v60, v132
	v_pk_mul_f32 v[60:61], v[132:133], v[60:61] op_sel:[1,0]
	v_pk_mul_f32 v[58:59], v[132:133], v[58:59] op_sel:[1,0]
	v_pk_fma_f32 v[60:61], v[84:85], v[60:61], v[94:95]
	v_pk_fma_f32 v[58:59], v[86:87], v[58:59], v[96:97]
	v_pk_fma_f32 v[56:57], v[56:57], v[72:73], v[60:61]
	v_pk_fma_f32 v[54:55], v[54:55], v[70:71], v[58:59]
;     __device__ __forceinline__ void operator()(const f32x4 (&acc)[2][2][4][2], const pg8::Unit& u, int wr, int wc, int, int) const { const int ln_ = lane_now(); const int fr = ln_ & 15, fq = ln_ >> 4;
;     ...
;                 for (int m = 0; m < 4; ++m) { const size_t row = (size_t)(upm * 256 + rl0 + ai * 128 + m * 16); tv[m] = *(const u32x4*)(H + row * D + c); st[m] = *(const f32x2*)(stats + row * 2); }
;                 asm volatile("s_waitcnt vmcnt(0)" ::: "memory");
; #pragma unroll
;                 for (int m = 0; m < 4; ++m) { const h16x4 ha = __builtin_bit_cast(h16x4, (u32x2){tv[m].x, tv[m].y}), hb = __builtin_bit_cast(h16x4, (u32x2){tv[m].z, tv[m].w});
;                     const f32x4 t0 = (f32x4){(float)ha[0], (float)ha[1], (float)ha[2], (float)ha[3]}, t1 = (f32x4){(float)hb[0], (float)hb[1], (float)hb[2], (float)hb[3]};
;                     const f32x4 o0 = (t0 - st[m].x) * st[m].y * g0 + b0 + gv0 * acc[ai][bj][m][0], o1 = (t1 - st[m].x) * st[m].y * g1 + b1 + gv1 * acc[ai][bj][m][1];
;                     h16x4 qa, qb; qa[0] = (_Float16)o0[0]; qa[1] = (_Float16)o0[1]; qa[2] = (_Float16)o0[2]; qa[3] = (_Float16)o0[3]; qb[0] = (_Float16)o1[0]; qb[1] = (_Float16)o1[1]; qb[2] = (_Float16)o1[2]; qb[3] = (_Float16)o1[3];
;                     const u32x2 pa = __builtin_bit_cast(u32x2, qa), pb = __builtin_bit_cast(u32x2, qb);
;                     *(u32x4*)(H + (size_t)(upm * 256 + rl0 + ai * 128 + m * 16) * D + c) = (u32x4){pa.x, pa.y, pb.x, pb.y}; } } }
	v_sub_f32_e32 v59, v63, v132
	v_sub_f32_e32 v58, v62, v132
	v_sub_f32_e32 v61, v65, v132
	v_sub_f32_e32 v60, v64, v132
	v_pk_mul_f32 v[60:61], v[132:133], v[60:61] op_sel:[1,0]
	v_pk_mul_f32 v[58:59], v[132:133], v[58:59] op_sel:[1,0]
	v_pk_fma_f32 v[60:61], v[78:79], v[60:61], v[88:89]
	v_pk_fma_f32 v[58:59], v[80:81], v[58:59], v[92:93]
	v_pk_fma_f32 v[52:53], v[52:53], v[68:69], v[60:61]
	v_pk_fma_f32 v[58:59], v[50:51], v[66:67], v[58:59]
	v_cvt_pk_f16_f32 v51, v56, v57
	v_cvt_pk_f16_f32 v50, v54, v55
	v_cvt_pk_f16_f32 v53, v52, v53
	v_cvt_pk_f16_f32 v52, v58, v59
	global_store_dwordx4 v[114:115], v[50:53], off offset:256
	v_cvt_f32_f16_e32 v54, v126
	v_cvt_f32_f16_sdwa v55, v126 dst_sel:DWORD dst_unused:UNUSED_PAD src0_sel:WORD_1
	v_cvt_f32_f16_e32 v50, v124
	v_cvt_f32_f16_sdwa v51, v124 dst_sel:DWORD dst_unused:UNUSED_PAD src0_sel:WORD_1
	v_cvt_f32_f16_e32 v52, v125
	v_cvt_f32_f16_sdwa v53, v125 dst_sel:DWORD dst_unused:UNUSED_PAD src0_sel:WORD_1
	v_cvt_f32_f16_e32 v56, v127
	v_cvt_f32_f16_sdwa v57, v127 dst_sel:DWORD dst_unused:UNUSED_PAD src0_sel:WORD_1
	v_sub_f32_e32 v51, v51, v134
	v_sub_f32_e32 v50, v50, v134
	v_sub_f32_e32 v53, v53, v134
	v_sub_f32_e32 v52, v52, v134
	v_pk_mul_f32 v[52:53], v[134:135], v[52:53] op_sel:[1,0]
	v_pk_mul_f32 v[50:51], v[134:135], v[50:51] op_sel:[1,0]
	v_pk_fma_f32 v[52:53], v[84:85], v[52:53], v[94:95]
	v_pk_fma_f32 v[50:51], v[86:87], v[50:51], v[96:97]
	v_pk_fma_f32 v[48:49], v[48:49], v[72:73], v[52:53]
	v_pk_fma_f32 v[46:47], v[46:47], v[70:71], v[50:51]
	v_sub_f32_e32 v51, v55, v134
	v_sub_f32_e32 v50, v54, v134
	v_sub_f32_e32 v53, v57, v134
	v_sub_f32_e32 v52, v56, v134
	v_pk_mul_f32 v[52:53], v[134:135], v[52:53] op_sel:[1,0]
	v_pk_mul_f32 v[50:51], v[134:135], v[50:51] op_sel:[1,0]
	v_pk_fma_f32 v[52:53], v[78:79], v[52:53], v[88:89]
	v_pk_fma_f32 v[50:51], v[80:81], v[50:51], v[92:93]
	v_pk_fma_f32 v[44:45], v[44:45], v[68:69], v[52:53]
	v_pk_fma_f32 v[50:51], v[42:43], v[66:67], v[50:51]
	v_cvt_pk_f16_f32 v43, v48, v49
	v_cvt_pk_f16_f32 v42, v46, v47
	v_cvt_pk_f16_f32 v45, v44, v45
	v_cvt_pk_f16_f32 v44, v50, v51
	global_store_dwordx4 v[106:107], v[42:45], off offset:256
	v_cvt_f32_f16_e32 v46, v130
	v_cvt_f32_f16_sdwa v47, v130 dst_sel:DWORD dst_unused:UNUSED_PAD src0_sel:WORD_1
	v_cvt_f32_f16_e32 v42, v128
	v_cvt_f32_f16_sdwa v43, v128 dst_sel:DWORD dst_unused:UNUSED_PAD src0_sel:WORD_1
	v_cvt_f32_f16_e32 v44, v129
	v_cvt_f32_f16_sdwa v45, v129 dst_sel:DWORD dst_unused:UNUSED_PAD src0_sel:WORD_1
	v_cvt_f32_f16_e32 v48, v131
	v_cvt_f32_f16_sdwa v49, v131 dst_sel:DWORD dst_unused:UNUSED_PAD src0_sel:WORD_1
	v_sub_f32_e32 v43, v43, v136
	v_sub_f32_e32 v42, v42, v136
	v_sub_f32_e32 v45, v45, v136
	v_sub_f32_e32 v44, v44, v136
	v_pk_mul_f32 v[44:45], v[136:137], v[44:45] op_sel:[1,0]
	v_pk_mul_f32 v[42:43], v[136:137], v[42:43] op_sel:[1,0]
	v_pk_fma_f32 v[44:45], v[84:85], v[44:45], v[94:95]
	v_pk_fma_f32 v[42:43], v[86:87], v[42:43], v[96:97]
	v_pk_fma_f32 v[40:41], v[40:41], v[72:73], v[44:45]
	v_pk_fma_f32 v[38:39], v[38:39], v[70:71], v[42:43]
	v_sub_f32_e32 v43, v47, v136
	v_sub_f32_e32 v42, v46, v136
	v_sub_f32_e32 v45, v49, v136
	v_sub_f32_e32 v44, v48, v136
	v_pk_mul_f32 v[44:45], v[136:137], v[44:45] op_sel:[1,0]
	v_pk_mul_f32 v[42:43], v[136:137], v[42:43] op_sel:[1,0]
	v_pk_fma_f32 v[44:45], v[78:79], v[44:45], v[88:89]
	v_pk_fma_f32 v[42:43], v[80:81], v[42:43], v[92:93]
	v_pk_fma_f32 v[36:37], v[36:37], v[68:69], v[44:45]
	v_pk_fma_f32 v[42:43], v[34:35], v[66:67], v[42:43]
	v_cvt_pk_f16_f32 v35, v40, v41
	v_cvt_pk_f16_f32 v34, v38, v39
	v_cvt_pk_f16_f32 v37, v36, v37
	v_cvt_pk_f16_f32 v36, v42, v43
	global_store_dwordx4 v[100:101], v[34:37], off offset:256
	s_waitcnt vmcnt(4)
;     __device__ __forceinline__ void operator()(const f32x4 (&acc)[2][2][4][2], const pg8::Unit& u, int wr, int wc, int, int) const { const int ln_ = lane_now(); const int fr = ln_ & 15, fq = ln_ >> 4;
;     ...
; #pragma unroll
;                 for (int m = 0; m < 4; ++m) { const h16x4 ha = __builtin_bit_cast(h16x4, (u32x2){tv[m].x, tv[m].y}), hb = __builtin_bit_cast(h16x4, (u32x2){tv[m].z, tv[m].w});
;                     const f32x4 t0 = (f32x4){(float)ha[0], (float)ha[1], (float)ha[2], (float)ha[3]}, t1 = (f32x4){(float)hb[0], (float)hb[1], (float)hb[2], (float)hb[3]};
;                     const f32x4 o0 = (t0 - st[m].x) * st[m].y * g0 + b0 + gv0 * acc[ai][bj][m][0], o1 = (t1 - st[m].x) * st[m].y * g1 + b1 + gv1 * acc[ai][bj][m][1];
;                     h16x4 qa, qb; qa[0] = (_Float16)o0[0]; qa[1] = (_Float16)o0[1]; qa[2] = (_Float16)o0[2]; qa[3] = (_Float16)o0[3]; qb[0] = (_Float16)o1[0]; qb[1] = (_Float16)o1[1]; qb[2] = (_Float16)o1[2]; qb[3] = (_Float16)o1[3];
;                     const u32x2 pa = __builtin_bit_cast(u32x2, qa), pb = __builtin_bit_cast(u32x2, qb);
;                     *(u32x4*)(H + (size_t)(upm * 256 + rl0 + ai * 128 + m * 16) * D + c) = (u32x4){pa.x, pa.y, pb.x, pb.y}; } } }
	s_nop 1
	v_mov_b32_e32 v34, v240
	v_mov_b32_e32 v35, v241
	v_mov_b32_e32 v36, v242
	v_mov_b32_e32 v37, v243
	v_mov_b32_e32 v50, v226
	v_mov_b32_e32 v51, v227
	v_mov_b32_e32 v38, v244
	v_mov_b32_e32 v39, v245
	v_mov_b32_e32 v40, v246
	v_mov_b32_e32 v41, v247
	v_mov_b32_e32 v52, v228
	v_mov_b32_e32 v53, v229
	v_mov_b32_e32 v42, v248
	v_mov_b32_e32 v43, v249
	v_mov_b32_e32 v44, v250
	v_mov_b32_e32 v45, v251
	v_mov_b32_e32 v54, v236
	v_mov_b32_e32 v55, v237
	v_mov_b32_e32 v46, v232
	v_mov_b32_e32 v47, v233
	v_mov_b32_e32 v48, v234
	v_mov_b32_e32 v49, v235
	v_mov_b32_e32 v56, v238
	v_mov_b32_e32 v57, v217
	v_cvt_f32_f16_e32 v58, v34
	v_cvt_f32_f16_sdwa v34, v34 dst_sel:DWORD dst_unused:UNUSED_PAD src0_sel:WORD_1
	v_cvt_f32_f16_e32 v59, v35
	v_cvt_f32_f16_sdwa v60, v35 dst_sel:DWORD dst_unused:UNUSED_PAD src0_sel:WORD_1
	v_cvt_f32_f16_e32 v61, v36
	v_cvt_f32_f16_sdwa v62, v36 dst_sel:DWORD dst_unused:UNUSED_PAD src0_sel:WORD_1
	v_cvt_f32_f16_e32 v63, v37
	v_cvt_f32_f16_sdwa v64, v37 dst_sel:DWORD dst_unused:UNUSED_PAD src0_sel:WORD_1
	v_sub_f32_e32 v35, v34, v50
	v_sub_f32_e32 v34, v58, v50
	v_sub_f32_e32 v37, v60, v50
	v_sub_f32_e32 v36, v59, v50
	v_pk_mul_f32 v[36:37], v[50:51], v[36:37] op_sel:[1,0]
	v_pk_mul_f32 v[34:35], v[50:51], v[34:35] op_sel:[1,0]
	v_pk_fma_f32 v[36:37], v[84:85], v[36:37], v[94:95]
	v_pk_fma_f32 v[34:35], v[86:87], v[34:35], v[96:97]
	v_pk_fma_f32 v[32:33], v[32:33], v[72:73], v[36:37]
	v_pk_fma_f32 v[30:31], v[30:31], v[70:71], v[34:35]
	v_sub_f32_e32 v35, v62, v50
	v_sub_f32_e32 v34, v61, v50
	v_sub_f32_e32 v37, v64, v50
	v_sub_f32_e32 v36, v63, v50
	v_pk_mul_f32 v[36:37], v[50:51], v[36:37] op_sel:[1,0]
	v_pk_mul_f32 v[34:35], v[50:51], v[34:35] op_sel:[1,0]
	v_pk_fma_f32 v[36:37], v[78:79], v[36:37], v[88:89]
	v_pk_fma_f32 v[34:35], v[80:81], v[34:35], v[92:93]
	v_pk_fma_f32 v[28:29], v[28:29], v[68:69], v[36:37]
	v_pk_fma_f32 v[34:35], v[26:27], v[66:67], v[34:35]
	v_cvt_pk_f16_f32 v27, v32, v33
	v_cvt_pk_f16_f32 v26, v30, v31
	v_cvt_pk_f16_f32 v29, v28, v29
	v_cvt_pk_f16_f32 v28, v34, v35
	global_store_dwordx4 v[90:91], v[26:29], off offset:256
	v_cvt_f32_f16_e32 v30, v40
	v_cvt_f32_f16_sdwa v31, v40 dst_sel:DWORD dst_unused:UNUSED_PAD src0_sel:WORD_1
	v_cvt_f32_f16_e32 v26, v38
	v_cvt_f32_f16_sdwa v27, v38 dst_sel:DWORD dst_unused:UNUSED_PAD src0_sel:WORD_1
	v_cvt_f32_f16_e32 v28, v39
	v_cvt_f32_f16_sdwa v29, v39 dst_sel:DWORD dst_unused:UNUSED_PAD src0_sel:WORD_1
	v_cvt_f32_f16_e32 v32, v41
	v_cvt_f32_f16_sdwa v33, v41 dst_sel:DWORD dst_unused:UNUSED_PAD src0_sel:WORD_1
	v_sub_f32_e32 v27, v27, v52
	v_sub_f32_e32 v26, v26, v52
	v_sub_f32_e32 v29, v29, v52
	v_sub_f32_e32 v28, v28, v52
	v_pk_mul_f32 v[28:29], v[52:53], v[28:29] op_sel:[1,0]
	v_pk_mul_f32 v[26:27], v[52:53], v[26:27] op_sel:[1,0]
	v_pk_fma_f32 v[28:29], v[84:85], v[28:29], v[94:95]
	v_pk_fma_f32 v[26:27], v[86:87], v[26:27], v[96:97]
	v_pk_fma_f32 v[24:25], v[24:25], v[72:73], v[28:29]
	v_pk_fma_f32 v[22:23], v[22:23], v[70:71], v[26:27]
	v_sub_f32_e32 v27, v31, v52
	v_sub_f32_e32 v26, v30, v52
	v_sub_f32_e32 v29, v33, v52
	v_sub_f32_e32 v28, v32, v52
	v_pk_mul_f32 v[28:29], v[52:53], v[28:29] op_sel:[1,0]
	v_pk_mul_f32 v[26:27], v[52:53], v[26:27] op_sel:[1,0]
	v_pk_fma_f32 v[28:29], v[78:79], v[28:29], v[88:89]
	v_pk_fma_f32 v[26:27], v[80:81], v[26:27], v[92:93]
	v_pk_fma_f32 v[20:21], v[20:21], v[68:69], v[28:29]
	v_pk_fma_f32 v[26:27], v[18:19], v[66:67], v[26:27]
	v_cvt_pk_f16_f32 v19, v24, v25
	v_cvt_pk_f16_f32 v18, v22, v23
	v_cvt_pk_f16_f32 v21, v20, v21
	v_cvt_pk_f16_f32 v20, v26, v27
	global_store_dwordx4 v[82:83], v[18:21], off offset:256
	v_cvt_f32_f16_e32 v22, v44
	v_cvt_f32_f16_sdwa v23, v44 dst_sel:DWORD dst_unused:UNUSED_PAD src0_sel:WORD_1
	v_cvt_f32_f16_e32 v18, v42
	v_cvt_f32_f16_sdwa v19, v42 dst_sel:DWORD dst_unused:UNUSED_PAD src0_sel:WORD_1
	v_cvt_f32_f16_e32 v20, v43
	v_cvt_f32_f16_sdwa v21, v43 dst_sel:DWORD dst_unused:UNUSED_PAD src0_sel:WORD_1
	v_cvt_f32_f16_e32 v24, v45
	v_cvt_f32_f16_sdwa v25, v45 dst_sel:DWORD dst_unused:UNUSED_PAD src0_sel:WORD_1
	v_sub_f32_e32 v19, v19, v54
	v_sub_f32_e32 v18, v18, v54
	v_sub_f32_e32 v21, v21, v54
	v_sub_f32_e32 v20, v20, v54
	v_pk_mul_f32 v[20:21], v[54:55], v[20:21] op_sel:[1,0]
	v_pk_mul_f32 v[18:19], v[54:55], v[18:19] op_sel:[1,0]
	v_pk_fma_f32 v[20:21], v[84:85], v[20:21], v[94:95]
	v_pk_fma_f32 v[18:19], v[86:87], v[18:19], v[96:97]
	v_pk_fma_f32 v[16:17], v[16:17], v[72:73], v[20:21]
	v_pk_fma_f32 v[14:15], v[14:15], v[70:71], v[18:19]
	v_sub_f32_e32 v19, v23, v54
	v_sub_f32_e32 v18, v22, v54
	v_sub_f32_e32 v21, v25, v54
	v_sub_f32_e32 v20, v24, v54
	v_pk_mul_f32 v[20:21], v[54:55], v[20:21] op_sel:[1,0]
	v_pk_mul_f32 v[18:19], v[54:55], v[18:19] op_sel:[1,0]
	v_pk_fma_f32 v[20:21], v[78:79], v[20:21], v[88:89]
	v_pk_fma_f32 v[18:19], v[80:81], v[18:19], v[92:93]
	v_pk_fma_f32 v[12:13], v[12:13], v[68:69], v[20:21]
	v_pk_fma_f32 v[18:19], v[10:11], v[66:67], v[18:19]
	v_cvt_pk_f16_f32 v11, v16, v17
	v_cvt_pk_f16_f32 v10, v14, v15
	v_cvt_pk_f16_f32 v13, v12, v13
	v_cvt_pk_f16_f32 v12, v18, v19
	global_store_dwordx4 v[74:75], v[10:13], off offset:256
	v_cvt_f32_f16_e32 v14, v48
	v_cvt_f32_f16_sdwa v15, v48 dst_sel:DWORD dst_unused:UNUSED_PAD src0_sel:WORD_1
	v_cvt_f32_f16_e32 v10, v46
	v_cvt_f32_f16_sdwa v11, v46 dst_sel:DWORD dst_unused:UNUSED_PAD src0_sel:WORD_1
	v_cvt_f32_f16_e32 v12, v47
	v_cvt_f32_f16_sdwa v13, v47 dst_sel:DWORD dst_unused:UNUSED_PAD src0_sel:WORD_1
	v_cvt_f32_f16_e32 v16, v49
	v_cvt_f32_f16_sdwa v17, v49 dst_sel:DWORD dst_unused:UNUSED_PAD src0_sel:WORD_1
	v_sub_f32_e32 v11, v11, v56
	v_sub_f32_e32 v10, v10, v56
	v_sub_f32_e32 v13, v13, v56
	v_sub_f32_e32 v12, v12, v56
	v_pk_mul_f32 v[12:13], v[56:57], v[12:13] op_sel:[1,0]
	v_pk_mul_f32 v[10:11], v[56:57], v[10:11] op_sel:[1,0]
	v_pk_fma_f32 v[12:13], v[84:85], v[12:13], v[94:95]
	v_pk_fma_f32 v[10:11], v[86:87], v[10:11], v[96:97]
	v_pk_fma_f32 v[8:9], v[8:9], v[72:73], v[12:13]
	v_pk_fma_f32 v[6:7], v[6:7], v[70:71], v[10:11]
	v_sub_f32_e32 v11, v15, v56
	v_sub_f32_e32 v10, v14, v56
	v_sub_f32_e32 v13, v17, v56
	v_sub_f32_e32 v12, v16, v56
	v_pk_mul_f32 v[12:13], v[56:57], v[12:13] op_sel:[1,0]
	v_pk_mul_f32 v[10:11], v[56:57], v[10:11] op_sel:[1,0]
	v_pk_fma_f32 v[12:13], v[78:79], v[12:13], v[88:89]
	v_pk_fma_f32 v[10:11], v[80:81], v[10:11], v[92:93]
	v_pk_fma_f32 v[4:5], v[4:5], v[68:69], v[12:13]
	v_pk_fma_f32 v[10:11], v[2:3], v[66:67], v[10:11]
	v_cvt_pk_f16_f32 v3, v8, v9
	v_cvt_pk_f16_f32 v2, v6, v7
	v_cvt_pk_f16_f32 v5, v4, v5
	v_cvt_pk_f16_f32 v4, v10, v11
	global_store_dwordx4 v[76:77], v[2:5], off offset:256
